# speedup vs baseline: 1.0548x; 1.0022x over previous
; template <int NS, bool LN, bool WF32, bool WBF, int SKMODE>
; DI_ void row_pass(const float* Xin, float* Xout, bf16_t* XBo, const float* g, const float* b, const float* WsT, float* sk_out, const float* sk_bias, int row0, int nrows, int gw, int NGW, int lane) {
;     ...
;             for (int grp = 0; grp < NS / 8; ++grp) {
;                 float a[8];
; #pragma unroll
;                 for (int jc = 0; jc < 8; ++jc) {
;                     float s = 0.f;
; #pragma unroll
;                     for (int j = 0; j < 4; ++j) { const f32x4 w = *(const f32x4*)(WsT + (8 * grp + jc) * WST + 4 * (lane + 64 * j)); s += (v[j][0] * w[0] + v[j][1] * w[1]) + (v[j][2] * w[2] + v[j][3] * w[3]); }
;                     a[jc] = s;
;                 }
.LBB0_473:
	s_waitcnt lgkmcnt(0)
	ds_read_b128 v[0:3], v236
	ds_read_b128 v[4:7], v236 offset:1024
	ds_read_b128 v[8:11], v236 offset:2048
	ds_read_b128 v[12:15], v236 offset:3072
	ds_read_b128 v[16:19], v236 offset:4112
	ds_read_b128 v[20:23], v236 offset:5136
	ds_read_b128 v[24:27], v236 offset:6160
	ds_read_b128 v[28:31], v236 offset:7184
	ds_read_b128 v[32:35], v236 offset:8224
	ds_read_b128 v[36:39], v236 offset:9248
	ds_read_b128 v[40:43], v236 offset:10272
	ds_read_b128 v[44:47], v236 offset:11296
	ds_read_b128 v[50:53], v236 offset:12336
	ds_read_b128 v[54:57], v236 offset:13360
	ds_read_b128 v[58:61], v236 offset:14384
	ds_read_b128 v[62:65], v236 offset:15408
	s_waitcnt lgkmcnt(15)
	v_mul_f32_e32 v242, v1, v149
	v_mul_f32_e32 v243, v3, v151
	v_fmac_f32_e32 v242, v0, v148
	v_fmac_f32_e32 v243, v2, v150
	v_add_f32_e32 v242, v242, v243
	v_add_f32_e32 v244, 0, v242
	ds_read_b128 v[66:69], v236 offset:16448
	s_waitcnt lgkmcnt(15)
	v_mul_f32_e32 v242, v5, v153
	v_mul_f32_e32 v243, v7, v155
	v_fmac_f32_e32 v242, v4, v152
	v_fmac_f32_e32 v243, v6, v154
	v_add_f32_e32 v242, v242, v243
	v_add_f32_e32 v244, v244, v242
	ds_read_b128 v[70:73], v236 offset:17472
	s_waitcnt lgkmcnt(15)
	v_mul_f32_e32 v242, v9, v157
	v_mul_f32_e32 v243, v11, v159
	v_fmac_f32_e32 v242, v8, v156
	v_fmac_f32_e32 v243, v10, v158
	v_add_f32_e32 v242, v242, v243
	v_add_f32_e32 v244, v244, v242
	ds_read_b128 v[74:77], v236 offset:18496
	s_waitcnt lgkmcnt(15)
	v_mul_f32_e32 v242, v13, v161
	v_mul_f32_e32 v243, v15, v163
	v_fmac_f32_e32 v242, v12, v160
	v_fmac_f32_e32 v243, v14, v162
	v_add_f32_e32 v242, v242, v243
	v_add_f32_e32 v237, v244, v242
	ds_read_b128 v[78:81], v236 offset:19520
	s_waitcnt lgkmcnt(15)
	v_mul_f32_e32 v242, v17, v149
	v_mul_f32_e32 v243, v19, v151
	v_fmac_f32_e32 v242, v16, v148
	v_fmac_f32_e32 v243, v18, v150
	v_add_f32_e32 v242, v242, v243
	v_add_f32_e32 v244, 0, v242
	ds_read_b128 v[82:85], v236 offset:20560
	s_waitcnt lgkmcnt(15)
	v_mul_f32_e32 v242, v21, v153
	v_mul_f32_e32 v243, v23, v155
	v_fmac_f32_e32 v242, v20, v152
	v_fmac_f32_e32 v243, v22, v154
	v_add_f32_e32 v242, v242, v243
	v_add_f32_e32 v244, v244, v242
	ds_read_b128 v[86:89], v236 offset:21584
	s_waitcnt lgkmcnt(15)
	v_mul_f32_e32 v242, v25, v157
	v_mul_f32_e32 v243, v27, v159
	v_fmac_f32_e32 v242, v24, v156
	v_fmac_f32_e32 v243, v26, v158
	v_add_f32_e32 v242, v242, v243
	v_add_f32_e32 v244, v244, v242
	ds_read_b128 v[90:93], v236 offset:22608
	s_waitcnt lgkmcnt(15)
	v_mul_f32_e32 v242, v29, v161
	v_mul_f32_e32 v243, v31, v163
	v_fmac_f32_e32 v242, v28, v160
	v_fmac_f32_e32 v243, v30, v162
	v_add_f32_e32 v242, v242, v243
	v_add_f32_e32 v238, v244, v242
	ds_read_b128 v[94:97], v236 offset:23632
	s_waitcnt lgkmcnt(15)
	v_mul_f32_e32 v242, v33, v149
	v_mul_f32_e32 v243, v35, v151
	v_fmac_f32_e32 v242, v32, v148
	v_fmac_f32_e32 v243, v34, v150
	v_add_f32_e32 v242, v242, v243
	v_add_f32_e32 v244, 0, v242
	ds_read_b128 v[98:101], v236 offset:24672
	s_waitcnt lgkmcnt(15)
	v_mul_f32_e32 v242, v37, v153
	v_mul_f32_e32 v243, v39, v155
	v_fmac_f32_e32 v242, v36, v152
	v_fmac_f32_e32 v243, v38, v154
	v_add_f32_e32 v242, v242, v243
	v_add_f32_e32 v244, v244, v242
	ds_read_b128 v[102:105], v236 offset:25696
	s_waitcnt lgkmcnt(15)
	v_mul_f32_e32 v242, v41, v157
	v_mul_f32_e32 v243, v43, v159
	v_fmac_f32_e32 v242, v40, v156
	v_fmac_f32_e32 v243, v42, v158
	v_add_f32_e32 v242, v242, v243
	v_add_f32_e32 v244, v244, v242
	ds_read_b128 v[106:109], v236 offset:26720
	s_waitcnt lgkmcnt(15)
	v_mul_f32_e32 v242, v45, v161
	v_mul_f32_e32 v243, v47, v163
	v_fmac_f32_e32 v242, v44, v160
	v_fmac_f32_e32 v243, v46, v162
	v_add_f32_e32 v242, v242, v243
	v_add_f32_e32 v239, v244, v242
	ds_read_b128 v[110:113], v236 offset:27744
	s_waitcnt lgkmcnt(15)
	v_mul_f32_e32 v242, v51, v149
	v_mul_f32_e32 v243, v53, v151
	v_fmac_f32_e32 v242, v50, v148
	v_fmac_f32_e32 v243, v52, v150
	v_add_f32_e32 v242, v242, v243
	v_add_f32_e32 v244, 0, v242
	ds_read_b128 v[114:117], v236 offset:28784
	s_waitcnt lgkmcnt(15)
	v_mul_f32_e32 v242, v55, v153
	v_mul_f32_e32 v243, v57, v155
	v_fmac_f32_e32 v242, v54, v152
	v_fmac_f32_e32 v243, v56, v154
	v_add_f32_e32 v242, v242, v243
	v_add_f32_e32 v244, v244, v242
	ds_read_b128 v[118:121], v236 offset:29808
	s_waitcnt lgkmcnt(15)
	v_mul_f32_e32 v242, v59, v157
	v_mul_f32_e32 v243, v61, v159
	v_fmac_f32_e32 v242, v58, v156
	v_fmac_f32_e32 v243, v60, v158
	v_add_f32_e32 v242, v242, v243
	v_add_f32_e32 v244, v244, v242
	ds_read_b128 v[122:125], v236 offset:30832
	s_waitcnt lgkmcnt(15)
	v_mul_f32_e32 v242, v63, v161
	v_mul_f32_e32 v243, v65, v163
	v_fmac_f32_e32 v242, v62, v160
	v_fmac_f32_e32 v243, v64, v162
	v_add_f32_e32 v242, v242, v243
	v_add_f32_e32 v240, v244, v242
	ds_read_b128 v[126:129], v236 offset:31856
	s_waitcnt lgkmcnt(15)
	v_mul_f32_e32 v242, v67, v149
	v_mul_f32_e32 v243, v69, v151
	v_fmac_f32_e32 v242, v66, v148
	v_fmac_f32_e32 v243, v68, v150
	v_add_f32_e32 v242, v242, v243
	v_add_f32_e32 v244, 0, v242
	s_waitcnt lgkmcnt(14)
; template <int NS>
; DI_ void skinny_pass_bf16(const bf16_t* XBrows, int nrows, const float* WsT, float* sk_out, int gw, int NGW, int lane) {
;     ...
;         for (int grp = 0; grp < NS / 8; ++grp) {
;             float a[4][8];
; #pragma unroll
;             for (int jc = 0; jc < 8; ++jc) {
;                 const float* wp = WsT + (8 * grp + jc) * WST + 4 * lane; float s0 = 0.f, s1 = 0.f, s2 = 0.f, s3 = 0.f;
; #pragma unroll
;                 for (int j = 0; j < 4; ++j) { const f32x4 w = *(const f32x4*)(wp + 256 * j);
;                     s0 += (v[0][4 * j] * w[0] + v[0][4 * j + 1] * w[1]) + (v[0][4 * j + 2] * w[2] + v[0][4 * j + 3] * w[3]);
;                     s1 += (v[1][4 * j] * w[0] + v[1][4 * j + 1] * w[1]) + (v[1][4 * j + 2] * w[2] + v[1][4 * j + 3] * w[3]);
;                     s2 += (v[2][4 * j] * w[0] + v[2][4 * j + 1] * w[1]) + (v[2][4 * j + 2] * w[2] + v[2][4 * j + 3] * w[3]);
;                     s3 += (v[3][4 * j] * w[0] + v[3][4 * j + 1] * w[1]) + (v[3][4 * j + 2] * w[2] + v[3][4 * j + 3] * w[3]); }
;                 a[0][jc] = s0; a[1][jc] = s1; a[2][jc] = s2; a[3][jc] = s3;
;             }
; #pragma unroll
;             for (int r = 0; r < 4; ++r) {
;                 { const bool up = (lane & 32) != 0;
; #pragma unroll
;                   for (int i = 0; i < 4; ++i) { const float send = up ? a[r][i] : a[r][4 + i], keep = up ? a[r][4 + i] : a[r][i]; a[r][i] = keep + __shfl_xor(send, 32); } }
;                 { const bool up = (lane & 16) != 0;
; #pragma unroll
;                   for (int i = 0; i < 2; ++i) { const float send = up ? a[r][i] : a[r][2 + i], keep = up ? a[r][2 + i] : a[r][i]; a[r][i] = keep + __shfl_xor(send, 16); } }
;                 { const bool up = (lane & 8) != 0; const float send = up ? a[r][0] : a[r][1], keep = up ? a[r][1] : a[r][0]; a[r][0] = keep + __shfl_xor(send, 8); }
;                 a[r][0] += __shfl_xor(a[r][0], 4); a[r][0] += __shfl_xor(a[r][0], 2); a[r][0] += __shfl_xor(a[r][0], 1);
;                 if ((lane & 7) == 0 && row + r * NGW < nrows) sk_out[(size_t)(row + r * NGW) * NS + 8 * grp + (lane >> 3)] = a[r][0];
	v_mul_f32_e32 v242, v71, v153
	v_mul_f32_e32 v243, v73, v155
	v_fmac_f32_e32 v242, v70, v152
	v_fmac_f32_e32 v243, v72, v154
	v_add_f32_e32 v242, v242, v243
	v_add_f32_e32 v244, v244, v242
	s_waitcnt lgkmcnt(13)
	v_mul_f32_e32 v242, v75, v157
	v_mul_f32_e32 v243, v77, v159
	v_fmac_f32_e32 v242, v74, v156
	v_fmac_f32_e32 v243, v76, v158
	v_add_f32_e32 v242, v242, v243
	v_add_f32_e32 v244, v244, v242
	s_waitcnt lgkmcnt(12)
	v_mul_f32_e32 v242, v79, v161
	v_mul_f32_e32 v243, v81, v163
	v_fmac_f32_e32 v242, v78, v160
	v_fmac_f32_e32 v243, v80, v162
	v_add_f32_e32 v242, v242, v243
	v_add_f32_e32 v241, v244, v242
	s_waitcnt lgkmcnt(11)
	v_mul_f32_e32 v242, v83, v149
	v_mul_f32_e32 v243, v85, v151
	v_fmac_f32_e32 v242, v82, v148
	v_fmac_f32_e32 v243, v84, v150
	v_add_f32_e32 v242, v242, v243
	v_add_f32_e32 v244, 0, v242
	s_waitcnt lgkmcnt(10)
	v_mul_f32_e32 v242, v87, v153
	v_mul_f32_e32 v243, v89, v155
	v_fmac_f32_e32 v242, v86, v152
	v_fmac_f32_e32 v243, v88, v154
	v_add_f32_e32 v242, v242, v243
	v_add_f32_e32 v244, v244, v242
	s_waitcnt lgkmcnt(9)
	v_mul_f32_e32 v242, v91, v157
	v_mul_f32_e32 v243, v93, v159
	v_fmac_f32_e32 v242, v90, v156
	v_fmac_f32_e32 v243, v92, v158
	v_add_f32_e32 v242, v242, v243
	v_add_f32_e32 v244, v244, v242
	s_waitcnt lgkmcnt(8)
	v_mul_f32_e32 v242, v95, v161
	v_mul_f32_e32 v243, v97, v163
	v_fmac_f32_e32 v242, v94, v160
	v_fmac_f32_e32 v243, v96, v162
	v_add_f32_e32 v242, v242, v243
	v_add_f32_e32 v194, v244, v242
	s_waitcnt lgkmcnt(7)
	v_mul_f32_e32 v242, v99, v149
	v_mul_f32_e32 v243, v101, v151
	v_fmac_f32_e32 v242, v98, v148
	v_fmac_f32_e32 v243, v100, v150
	v_add_f32_e32 v242, v242, v243
	v_add_f32_e32 v244, 0, v242
	s_waitcnt lgkmcnt(6)
	v_mul_f32_e32 v242, v103, v153
	v_mul_f32_e32 v243, v105, v155
	v_fmac_f32_e32 v242, v102, v152
	v_fmac_f32_e32 v243, v104, v154
	v_add_f32_e32 v242, v242, v243
	v_add_f32_e32 v244, v244, v242
	s_waitcnt lgkmcnt(5)
	v_mul_f32_e32 v242, v107, v157
	v_mul_f32_e32 v243, v109, v159
	v_fmac_f32_e32 v242, v106, v156
	v_fmac_f32_e32 v243, v108, v158
	v_add_f32_e32 v242, v242, v243
	v_add_f32_e32 v244, v244, v242
	s_waitcnt lgkmcnt(4)
	v_mul_f32_e32 v242, v111, v161
	v_mul_f32_e32 v243, v113, v163
	v_fmac_f32_e32 v242, v110, v160
	v_fmac_f32_e32 v243, v112, v162
	v_add_f32_e32 v242, v242, v243
	v_add_f32_e32 v195, v244, v242
	s_waitcnt lgkmcnt(3)
	v_mul_f32_e32 v242, v115, v149
	v_mul_f32_e32 v243, v117, v151
	v_fmac_f32_e32 v242, v114, v148
	v_fmac_f32_e32 v243, v116, v150
	v_add_f32_e32 v242, v242, v243
	v_add_f32_e32 v244, 0, v242
	s_waitcnt lgkmcnt(2)
	v_mul_f32_e32 v242, v119, v153
	v_mul_f32_e32 v243, v121, v155
	v_fmac_f32_e32 v242, v118, v152
	v_fmac_f32_e32 v243, v120, v154
	v_add_f32_e32 v242, v242, v243
	v_add_f32_e32 v244, v244, v242
	s_waitcnt lgkmcnt(1)
	v_mul_f32_e32 v242, v123, v157
	v_mul_f32_e32 v243, v125, v159
	v_fmac_f32_e32 v242, v122, v156
	v_fmac_f32_e32 v243, v124, v158
	v_add_f32_e32 v242, v242, v243
	v_add_f32_e32 v244, v244, v242
	s_waitcnt lgkmcnt(0)
	v_mul_f32_e32 v242, v127, v161
	v_mul_f32_e32 v243, v129, v163
	v_fmac_f32_e32 v242, v126, v160
	v_fmac_f32_e32 v243, v128, v162
	v_add_f32_e32 v242, v242, v243
	v_add_f32_e32 v196, v244, v242
	v_cndmask_b32_e32 v197, v237, v241, vcc
	ds_bpermute_b32 v197, v142, v197
	v_cndmask_b32_e32 v198, v241, v237, vcc
	s_waitcnt lgkmcnt(0)
	v_add_f32_e32 v197, v198, v197
	v_cndmask_b32_e32 v198, v238, v194, vcc
	ds_bpermute_b32 v198, v142, v198
	v_cndmask_b32_e32 v194, v194, v238, vcc
	s_waitcnt lgkmcnt(0)
	v_add_f32_e32 v194, v194, v198
	v_cndmask_b32_e32 v198, v239, v195, vcc
	ds_bpermute_b32 v198, v142, v198
	v_cndmask_b32_e32 v195, v195, v239, vcc
	s_waitcnt lgkmcnt(0)
	v_add_f32_e32 v195, v195, v198
	v_cndmask_b32_e32 v198, v240, v196, vcc
	ds_bpermute_b32 v198, v142, v198
	v_cndmask_b32_e32 v196, v196, v240, vcc
	s_waitcnt lgkmcnt(0)
	v_add_f32_e32 v196, v196, v198
	v_cndmask_b32_e64 v198, v197, v195, s[38:39]
	v_cndmask_b32_e64 v195, v195, v197, s[38:39]
	ds_bpermute_b32 v197, v143, v198
	s_waitcnt lgkmcnt(0)
	v_add_f32_e32 v195, v195, v197
	v_cndmask_b32_e64 v197, v194, v196, s[38:39]
	v_cndmask_b32_e64 v194, v196, v194, s[38:39]
	ds_bpermute_b32 v196, v143, v197
	s_waitcnt lgkmcnt(0)
	v_add_f32_e32 v194, v194, v196
	v_cndmask_b32_e64 v196, v195, v194, s[42:43]
	v_cndmask_b32_e64 v194, v194, v195, s[42:43]
	ds_bpermute_b32 v195, v144, v196
	s_waitcnt lgkmcnt(0)
	v_add_f32_e32 v194, v194, v195
	ds_bpermute_b32 v195, v145, v194
	s_waitcnt lgkmcnt(0)
	v_add_f32_e32 v194, v194, v195
	ds_bpermute_b32 v195, v146, v194
	s_waitcnt lgkmcnt(0)
	v_add_f32_e32 v237, v194, v195
	ds_bpermute_b32 v238, v147, v237
	s_and_saveexec_b64 s[18:19], s[46:47]
	s_cbranch_execz .LBB0_475
	v_lshl_add_u64 v[240:241], v[134:135], 0, s[10:11]
	s_waitcnt lgkmcnt(0)
	v_add_f32_e32 v194, v237, v238
	global_store_dword v[240:241], v194, off
